# P6 GDN scan: per-chunk operands loaded cooperatively with full-line global loads and staged through LDS (one chunk ahead) instead of per-wave fragment loads
# speedup vs baseline: 1.0315x; 1.0315x over previous
; #define LAS __attribute__((address_space(3)))
; __device__ __forceinline__ float bf2f(unsigned short b) { return __uint_as_float((unsigned)b << 16); }
; __device__ __forceinline__ void scan_load(ScanFrag& f, int n, int b, int h, int ti, int s, int li, int lq, int ucol, const bf16* Qg, const bf16* Kg, const bf16* Vg, const bf16* KT, const bf16* QK, const float* GC) {
;     const int gcid = b * 32 + n, m0 = b * 2048 + n * 64;
;     const bf16* wrow = Kg + (size_t)(m0 + 16 * ti + li) * D + h * 128 + 8 * lq; const bf16* qrow = Qg + (size_t)(m0 + 16 * ti + li) * D + h * 128 + 8 * lq;
; #pragma unroll
;     for (int ks = 0; ks < 4; ++ks) { f.wA[ks] = *(const bf16x8*)(wrow + 32 * ks); f.qA[ks] = *(const bf16x8*)(qrow + 32 * ks); }
;     const bf16* qkrow = QK + ((size_t)(gcid * 8 + h) * 64 + 16 * ti + li) * 64 + 8 * lq; const bf16* ktrow = KT + ((size_t)(gcid * 8 + h) * 128 + 16 * s + li) * 64 + 8 * lq;
; #pragma unroll
;     for (int k2 = 0; k2 < 2; ++k2) { f.qkA[k2] = *(const bf16x8*)(qkrow + 32 * k2); f.kA[k2] = *(const bf16x8*)(ktrow + 32 * k2); }
;     const int rowb = m0 + 16 * ti + 4 * lq;
; #pragma unroll
;     for (int r = 0; r < 4; ++r) { f.uval[r] = bf2f(Vg[(size_t)(rowb + r) * D + ucol]); f.gcr[r] = GC[(size_t)(rowb + r) * 8 + h]; }
;     f.gl = GC[(size_t)(m0 + 63) * 8 + h];
; }
; __device__ __forceinline__ void scan_unit(LAS unsigned char* lds, int uidx, const bf16* Qg, const bf16* Kg, bf16* Vg, const bf16* KT, const bf16* QK, const float* GC, float* SSQ, float* sp_gdn) {
;     const int tid = threadIdx.x, lane = tid & 63, s = __builtin_amdgcn_readfirstlane(tid >> 6);
;     const int xc = uidx & 7, yy = uidx >> 3, slab = yy & 3, bh = xc * 8 + (yy >> 2), b = bh >> 3, h = bh & 7;
;     LAS bf16* St = (LAS bf16*)lds; LAS bf16* Vt = St + 2 * 32 * 136; LAS bf16* Vts = Vt + 32 * 72;
;     const int ti = s >> 1, c = s & 1, li = lane & 15, lq = lane >> 4;
;     f32x4 S0 = (f32x4){0.f, 0.f, 0.f, 0.f}, S1 = S0;
;     const int ucol = h * 128 + slab * 32 + 16 * c + li;
;     ScanFrag cur, nxt;
;     scan_load(cur, 0, b, h, ti, s, li, lq, ucol, Qg, Kg, Vg, KT, QK, GC);
;     ...
;     float* so = sp_gdn + ((size_t)(b * 8 + h) * 128 + 16 * s + 4 * lq) * 128 + slab * 32 + li;
; #pragma unroll
;     for (int r = 0; r < 4; ++r) { so[(size_t)r * 128] = S0[r]; so[(size_t)r * 128 + 16] = S1[r]; }
;     LDS_BARRIER();
.Lscan_store:
	s_ashr_i32 s7, s6, 31
	s_lshl_b64 s[0:1], s[6:7], 7
	s_add_u32 s0, s0, s35
	s_addc_u32 s1, s1, 0
	v_mov_b32_e32 v9, s1
	v_or_b32_e32 v8, s0, v70
	v_lshlrev_b64 v[8:9], 9, v[8:9]
	v_lshl_add_u64 v[8:9], s[14:15], 0, v[8:9]
	s_lshl_b32 s8, s37, 2
	v_lshl_add_u64 v[8:9], v[8:9], 0, s[8:9]
	v_lshlrev_b32_e32 v68, 2, v156
	v_lshl_add_u64 v[8:9], v[8:9], 0, v[68:69]
	v_lshl_add_u64 v[10:11], v[8:9], 0, s[12:13]
	v_add_co_u32_e64 v8, s[6:7], s3, v8
	s_add_i32 s36, s36, s88
	s_nop 0
	v_addc_co_u32_e64 v9, s[6:7], 0, v9, s[6:7]
	global_store_dword v[8:9], v4, off
	global_store_dword v[10:11], v0, off offset:64
	global_store_dword v[10:11], v5, off offset:512
	global_store_dword v[10:11], v1, off offset:576
	global_store_dword v[10:11], v6, off offset:1024
	global_store_dword v[10:11], v2, off offset:1088
	global_store_dword v[10:11], v7, off offset:1536
	global_store_dword v[10:11], v3, off offset:1600
	s_waitcnt lgkmcnt(0)
	s_barrier
	s_cmpk_gt_i32 s36, 0xff
	s_cbranch_scc1 .LBB0_851
.LBB0_832:
	s_mov_b64 s[0:1], s[56:57]
	s_load_dwordx2 s[0:1], s[0:1], 0x108
	s_mov_b64 s[6:7], s[56:57]
	s_load_dwordx2 s[6:7], s[6:7], 0x108
	s_mov_b64 s[14:15], s[56:57]
	s_waitcnt lgkmcnt(0)
	s_add_u32 s18, s0, 0x4bb0000
	s_addc_u32 s19, s1, 0
	s_mov_b64 s[0:1], s[56:57]
	s_add_u32 s22, s6, 0x6c30000
	s_load_dwordx2 s[20:21], s[14:15], 0x108
	s_addc_u32 s23, s7, 0
	s_load_dwordx2 s[0:1], s[0:1], 0x108
	s_mov_b64 s[6:7], s[56:57]
	s_load_dwordx2 s[6:7], s[6:7], 0x108
	s_mov_b64 s[14:15], s[56:57]
	s_load_dwordx2 s[24:25], s[14:15], 0x108
	s_waitcnt lgkmcnt(0)
	s_add_u32 s28, s0, 0xad30000
	s_addc_u32 s29, s1, 0
	s_add_u32 s30, s6, 0xcdb0000
	s_addc_u32 s31, s7, 0
	s_add_u32 s39, s24, 0xef34000
	s_mov_b64 s[0:1], s[56:57]
	s_addc_u32 s42, s25, 0
	s_lshl_b32 s6, s36, 3
	s_ashr_i32 s7, s36, 5
	s_load_dwordx2 s[26:27], s[0:1], 0x108
	v_readfirstlane_b32 s0, v154
	s_bfe_u32 s1, s36, 0x20003
	s_and_b32 s6, s6, 56
	s_and_b32 s38, s7, 7
	s_add_i32 s6, s6, s7
	s_bfe_u32 s17, s0, 0x10006
	s_lshl_b32 s7, s38, 7
	s_lshl_b32 s37, s1, 5
	s_lshr_b32 s40, s0, 6
	s_ashr_i32 s34, s6, 3
	v_lshl_or_b32 v34, s17, 4, v156
	s_or_b32 s7, s7, s37
	s_lshr_b32 s0, s0, 3
	v_or_b32_e32 v4, s7, v34
	s_lshl_b32 s16, s34, 11
	s_and_b32 s7, s0, 0x1ffffff0
	s_add_i32 s0, s7, s16
	v_or_b32_e32 v76, s0, v70
	v_lshlrev_b32_e32 v68, 1, v4
	v_or_b32_e32 v6, 1, v76
	v_lshl_add_u64 v[4:5], s[20:21], 0, v[68:69]
	v_ashrrev_i32_e32 v77, 31, v76
	v_ashrrev_i32_e32 v7, 31, v6
	v_or_b32_e32 v0, s0, v156
	v_lshl_add_u64 v[74:75], v[4:5], 0, s[10:11]
	v_lshlrev_b64 v[4:5], 11, v[76:77]
	v_lshlrev_b64 v[8:9], 11, v[6:7]
	s_lshl_b32 s20, s34, 8
	s_mov_b64 s[14:15], s[56:57]
	v_ashrrev_i32_e32 v1, 31, v0
	v_lshl_add_u64 v[4:5], v[74:75], 0, v[4:5]
	v_lshl_add_u64 v[8:9], v[74:75], 0, v[8:9]
	s_or_b32 s34, s20, s38
	v_lshlrev_b64 v[0:1], 11, v[0:1]
	v_or_b32_e32 v4, 2, v76
	v_or_b32_e32 v32, 3, v76
	s_ashr_i32 s35, s34, 31
	v_lshl_add_u64 v[2:3], s[22:23], 0, v[0:1]
	s_lshl_b32 s8, s38, 8
	v_lshl_add_u64 v[0:1], s[18:19], 0, v[0:1]
	v_ashrrev_i32_e32 v5, 31, v4
	v_ashrrev_i32_e32 v33, 31, v32
	s_lshl_b64 s[20:21], s[34:35], 6
	v_lshl_add_u64 v[0:1], v[0:1], 0, s[8:9]
	v_lshlrev_b64 v[8:9], 11, v[4:5]
	v_lshlrev_b64 v[10:11], 11, v[32:33]
	s_add_u32 s20, s20, s7
	v_lshl_add_u64 v[2:3], v[2:3], 0, s[8:9]
	v_lshl_add_u64 v[0:1], v[0:1], 0, v[72:73]
	v_lshl_add_u64 v[8:9], v[74:75], 0, v[8:9]
	v_lshl_add_u64 v[10:11], v[74:75], 0, v[10:11]
	s_addc_u32 s21, s21, 0
	v_lshl_add_u64 v[2:3], v[2:3], 0, v[72:73]
	v_mov_b32_e32 v1, s21
	v_or_b32_e32 v0, s20, v156
	s_lshl_b64 s[20:21], s[34:35], 7
	s_lshl_b32 s35, s40, 4
	s_add_u32 s20, s20, s35
	s_addc_u32 s21, s21, 0
	v_lshlrev_b64 v[0:1], 7, v[0:1]
	v_mov_b32_e32 v3, s21
	v_or_b32_e32 v2, s20, v156
	v_lshl_add_u64 v[0:1], s[30:31], 0, v[0:1]
	v_lshlrev_b64 v[2:3], 7, v[2:3]
	s_lshl_b32 s43, s38, 2
	v_lshl_add_u64 v[0:1], v[0:1], 0, v[72:73]
	v_lshl_add_u64 v[2:3], s[28:29], 0, v[2:3]
	s_add_u32 s20, s39, s43
	v_lshl_add_u64 v[2:3], v[2:3], 0, v[72:73]
	s_addc_u32 s21, s42, 0
	v_lshlrev_b64 v[0:1], 5, v[76:77]
	v_lshl_add_u64 v[0:1], s[20:21], 0, v[0:1]
	v_lshlrev_b64 v[0:1], 5, v[6:7]
	v_lshl_add_u64 v[0:1], s[20:21], 0, v[0:1]
	v_lshlrev_b64 v[0:1], 5, v[4:5]
	s_or_b32 s40, s16, 63
	v_lshl_add_u64 v[0:1], s[20:21], 0, v[0:1]
	s_ashr_i32 s41, s40, 31
	v_lshlrev_b64 v[0:1], 5, v[32:33]
	s_lshl_b64 s[40:41], s[40:41], 5
	v_lshl_add_u64 v[0:1], s[20:21], 0, v[0:1]
	s_add_u32 s40, s39, s40
	s_addc_u32 s41, s42, s41
	v_mov_b32_e32 v2, s43
	s_add_u32 s22, s22, s8
	s_addc_u32 s23, s23, 0
	v_mul_u32_u24_e32 v32, 0x48, v34
	s_add_u32 s18, s18, s8
	v_lshlrev_b32_e32 v32, 1, v32
	s_addc_u32 s19, s19, 0
	s_lshl_b32 s8, s7, 1
	v_add_u32_e32 v106, 0, v32
	v_add3_u32 v101, v106, s8, v98
	v_add3_u32 v100, v92, s8, v32
	s_lshl_b32 s8, s38, 5
	s_waitcnt lgkmcnt(0)
; #define LAS __attribute__((address_space(3)))
; __device__ __forceinline__ float bf2f(unsigned short b) { return __uint_as_float((unsigned)b << 16); }
; __device__ __forceinline__ void scan_load(ScanFrag& f, int n, int b, int h, int ti, int s, int li, int lq, int ucol, const bf16* Qg, const bf16* Kg, const bf16* Vg, const bf16* KT, const bf16* QK, const float* GC) {
;     const int gcid = b * 32 + n, m0 = b * 2048 + n * 64;
;     const bf16* wrow = Kg + (size_t)(m0 + 16 * ti + li) * D + h * 128 + 8 * lq; const bf16* qrow = Qg + (size_t)(m0 + 16 * ti + li) * D + h * 128 + 8 * lq;
; #pragma unroll
;     for (int ks = 0; ks < 4; ++ks) { f.wA[ks] = *(const bf16x8*)(wrow + 32 * ks); f.qA[ks] = *(const bf16x8*)(qrow + 32 * ks); }
;     const bf16* qkrow = QK + ((size_t)(gcid * 8 + h) * 64 + 16 * ti + li) * 64 + 8 * lq; const bf16* ktrow = KT + ((size_t)(gcid * 8 + h) * 128 + 16 * s + li) * 64 + 8 * lq;
; #pragma unroll
;     for (int k2 = 0; k2 < 2; ++k2) { f.qkA[k2] = *(const bf16x8*)(qkrow + 32 * k2); f.kA[k2] = *(const bf16x8*)(ktrow + 32 * k2); }
;     const int rowb = m0 + 16 * ti + 4 * lq;
; #pragma unroll
;     for (int r = 0; r < 4; ++r) { f.uval[r] = bf2f(Vg[(size_t)(rowb + r) * D + ucol]); f.gcr[r] = GC[(size_t)(rowb + r) * 8 + h]; }
;     f.gl = GC[(size_t)(m0 + 63) * 8 + h];
; }
; __device__ __forceinline__ void scan_unit(LAS unsigned char* lds, int uidx, const bf16* Qg, const bf16* Kg, bf16* Vg, const bf16* KT, const bf16* QK, const float* GC, float* SSQ, float* sp_gdn) {
;     const int tid = threadIdx.x, lane = tid & 63, s = __builtin_amdgcn_readfirstlane(tid >> 6);
;     const int xc = uidx & 7, yy = uidx >> 3, slab = yy & 3, bh = xc * 8 + (yy >> 2), b = bh >> 3, h = bh & 7;
;     LAS bf16* St = (LAS bf16*)lds; LAS bf16* Vt = St + 2 * 32 * 136; LAS bf16* Vts = Vt + 32 * 72;
;     const int ti = s >> 1, c = s & 1, li = lane & 15, lq = lane >> 4;
;     f32x4 S0 = (f32x4){0.f, 0.f, 0.f, 0.f}, S1 = S0;
;     const int ucol = h * 128 + slab * 32 + 16 * c + li;
;     ScanFrag cur, nxt;
;     scan_load(cur, 0, b, h, ti, s, li, lq, ucol, Qg, Kg, Vg, KT, QK, GC);
;     for (int n = 0; n < 32; ++n) {
;         const int m0 = b * 2048 + n * 64, rowb = m0 + 16 * ti + 4 * lq;
;         __builtin_amdgcn_sched_barrier(0);
;         if (n + 1 < 32) scan_load(nxt, n + 1, b, h, ti, s, li, lq, ucol, Qg, Kg, Vg, KT, QK, GC);
	s_add_u32 s8, s26, s8
	v_lshl_add_u64 v[80:81], s[18:19], 0, v[72:73]
	s_addc_u32 s18, s27, 0
	s_lshl_b32 s1, s1, 3
	s_add_u32 s1, s8, s1
	s_addc_u32 s8, s18, 0
	s_lshl_b32 s17, s17, 2
	s_add_u32 s1, s1, s17
	s_addc_u32 s8, s8, 0
	s_add_u32 s18, s1, 0xefb6000
	s_addc_u32 s19, s8, 0
	s_ashr_i32 s17, s16, 31
	s_lshl_b64 s[26:27], s[16:17], 5
	s_load_dwordx2 s[14:15], s[14:15], 0x100
	v_lshl_add_u64 v[78:79], s[22:23], 0, v[72:73]
	s_or_b32 s22, s34, 8
	s_or_b32 s1, s26, s43
	v_or_b32_e32 v0, s7, v156
	v_mov_b32_e32 v1, v71
	s_add_u32 s1, s24, s1
	v_lshl_add_u64 v[2:3], s[30:31], 0, v[72:73]
	v_or_b32_e32 v4, s35, v156
	v_mov_b32_e32 v5, v71
	v_lshlrev_b64 v[0:1], 7, v[0:1]
	s_addc_u32 s8, s25, s27
	v_lshl_add_u64 v[6:7], s[28:29], 0, v[72:73]
	v_lshl_add_u64 v[82:83], v[2:3], 0, v[0:1]
	v_lshlrev_b64 v[0:1], 7, v[4:5]
	s_add_u32 s24, s1, 0xef34fe0
	v_mul_u32_u24_e32 v105, 0x110, v34
	v_lshl_add_u64 v[84:85], v[6:7], 0, v[0:1]
	s_addc_u32 s25, s8, 0
	v_add_u32_e32 v107, s0, v97
	s_mov_b32 s8, 0
	s_mov_b32 s17, 0
	v_mov_b32_e32 v4, 0
	v_mov_b32_e32 v5, v69
	v_mov_b32_e32 v6, v69
	v_mov_b32_e32 v7, v69
	v_mov_b32_e32 v0, 0
	v_mov_b32_e32 v1, v69
	v_mov_b32_e32 v2, v69
	v_mov_b32_e32 v3, v69
	s_and_b32 s0, s36, 7
	s_bfe_u32 s1, s36, 0x30005
	s_bfe_u32 s22, s36, 0x20003
	s_lshl_b32 s38, s0, 22
	s_lshl_b32 s39, s1, 8
	s_add_u32 s38, s38, s39
	s_add_u32 s24, s86, 0x6c30000
	s_addc_u32 s25, s87, 0
	s_add_u32 s24, s24, s38
	s_addc_u32 s25, s25, 0
	s_add_u32 s26, s86, 0x4bb0000
	s_addc_u32 s27, s87, 0
	s_add_u32 s26, s26, s38
	s_addc_u32 s27, s27, 0
	s_lshl_b32 s39, s22, 6
	s_add_u32 s98, s86, 0x8cb0000
	s_addc_u32 s99, s87, 0
	s_add_u32 s98, s98, s38
	s_addc_u32 s99, s99, 0
	s_add_u32 s98, s98, s39
	s_addc_u32 s99, s99, 0
	s_lshl_b32 s39, s0, 8
	s_add_u32 s39, s39, s1
	s_lshl_b32 s40, s39, 14
	s_add_u32 s28, s86, 0xad30000
	s_addc_u32 s29, s87, 0
	s_add_u32 s28, s28, s40
	s_addc_u32 s29, s29, 0
	s_lshl_b32 s40, s39, 13
	s_add_u32 s30, s86, 0xcdb0000
	s_addc_u32 s31, s87, 0
	s_add_u32 s30, s30, s40
	s_addc_u32 s31, s31, 0
	s_lshl_b32 s40, s0, 16
	s_lshl_b32 s41, s1, 2
	s_add_u32 s40, s40, s41
	s_add_u32 s100, s86, 0xef34000
	s_addc_u32 s101, s87, 0
	s_add_u32 s100, s100, s40
	s_addc_u32 s101, s101, 0
	v_lshrrev_b32_e32 v176, 4, v154
	v_and_b32_e32 v177, 15, v154
	v_lshlrev_b32_e32 v177, 4, v177
	v_lshl_add_u32 v41, v176, 11, v177
	v_add_u32_e32 v42, 0x10000, v41
	v_mul_u32_u24_e32 v47, 0x110, v176
	v_add_u32_e32 v47, v47, v177
	v_add_u32_e32 v47, 0x6800, v47
	v_lshlrev_b32_e32 v43, 4, v154
	v_add_u32_e32 v44, 0x2000, v43
	v_lshrrev_b32_e32 v176, 3, v154
	v_and_b32_e32 v177, 7, v154
	v_lshlrev_b32_e32 v177, 4, v177
	v_mul_u32_u24_e32 v48, 0x90, v176
	v_add_u32_e32 v48, v48, v177
	v_add_u32_e32 v48, 0xf000, v48
	v_bfe_u32 v176, v154, 2, 6
	v_and_b32_e32 v177, 3, v154
	v_lshlrev_b32_e32 v177, 4, v177
	v_lshl_add_u32 v45, v176, 11, v177
	v_mul_u32_u24_e32 v49, 0x50, v176
	v_add_u32_e32 v49, v49, v177
	v_add_u32_e32 v49, 0x15c00, v49
	v_and_b32_e32 v176, 63, v154
	v_lshlrev_b32_e32 v46, 5, v176
	v_lshlrev_b32_e32 v50, 2, v176
	v_add_u32_e32 v50, 0x17000, v50
	v_lshrrev_b32_e32 v176, 7, v154
	v_and_b32_e32 v177, 15, v154
	v_lshl_add_u32 v176, v176, 4, v177
	v_bfe_u32 v178, v154, 4, 2
	v_lshlrev_b32_e32 v179, 4, v178
	v_mul_u32_u24_e32 v51, 0x110, v176
	v_add_u32_e32 v51, v51, v179
	v_add_u32_e32 v51, 0x6800, v51
	v_mul_u32_u24_e32 v52, 0x90, v176
	v_add_u32_e32 v52, v52, v179
	v_add_u32_e32 v52, 0x13800, v52
	v_lshrrev_b32_e32 v180, 6, v154
	v_lshl_add_u32 v180, v180, 4, v177
	v_mul_u32_u24_e32 v53, 0x90, v180
	v_add_u32_e32 v53, v53, v179
	v_add_u32_e32 v53, 0xf000, v53
	v_lshrrev_b32_e32 v180, 7, v154
	v_lshlrev_b32_e32 v180, 4, v180
	v_lshl_add_u32 v180, v178, 2, v180
	v_mul_u32_u24_e32 v54, 0x50, v180
	v_bfe_u32 v181, v154, 6, 1
	v_lshl_add_u32 v181, v181, 4, v177
	v_lshl_add_u32 v54, v181, 1, v54
	v_add_u32_e32 v54, 0x15c00, v54
	v_lshlrev_b32_e32 v55, 2, v180
	v_add_u32_e32 v55, 0x17000, v55
	v_mov_b32_e32 v174, 0x170fc
	global_load_dwordx4 v[8:11], v41, s[24:25]
	global_load_dwordx4 v[12:15], v42, s[24:25]
	global_load_dwordx4 v[16:19], v41, s[26:27]
	global_load_dwordx4 v[20:23], v42, s[26:27]
	global_load_dwordx4 v[24:27], v43, s[28:29]
	global_load_dwordx4 v[28:31], v44, s[28:29]
	global_load_dwordx4 v[32:35], v43, s[30:31]
	global_load_dwordx4 v[36:39], v45, s[98:99]
	global_load_dword v40, v46, s[100:101]
	s_waitcnt vmcnt(0)
	ds_write_b128 v47, v[8:11]
	ds_write_b128 v47, v[12:15] offset:8704
	ds_write_b128 v47, v[16:19] offset:17408
	ds_write_b128 v47, v[20:23] offset:26112
	ds_write_b128 v48, v[24:27]
	ds_write_b128 v48, v[28:31] offset:9216
	ds_write_b128 v48, v[32:35] offset:18432
	ds_write_b128 v49, v[36:39]
	ds_write_b32 v50, v40
	s_add_u32 s24, s24, 0x20000
	s_addc_u32 s25, s25, 0
	s_add_u32 s26, s26, 0x20000
	s_addc_u32 s27, s27, 0
	s_add_u32 s28, s28, 0x20000
	s_addc_u32 s29, s29, 0
	s_add_u32 s30, s30, 0x10000
	s_addc_u32 s31, s31, 0
	s_add_u32 s98, s98, 0x20000
	s_addc_u32 s99, s99, 0
	s_add_u32 s100, s100, 0x800
	s_addc_u32 s101, s101, 0
	global_load_dwordx4 v[8:11], v41, s[24:25]
	global_load_dwordx4 v[12:15], v42, s[24:25]
	global_load_dwordx4 v[16:19], v41, s[26:27]
	global_load_dwordx4 v[20:23], v42, s[26:27]
	global_load_dwordx4 v[24:27], v43, s[28:29]
	global_load_dwordx4 v[28:31], v44, s[28:29]
	global_load_dwordx4 v[32:35], v43, s[30:31]
	global_load_dwordx4 v[36:39], v45, s[98:99]
	global_load_dword v40, v46, s[100:101]
; #define LAS __attribute__((address_space(3)))
; __device__ __forceinline__ void scan_unit(LAS unsigned char* lds, int uidx, const bf16* Qg, const bf16* Kg, bf16* Vg, const bf16* KT, const bf16* QK, const float* GC, float* SSQ, float* sp_gdn) {
;     ...
;     for (int n = 0; n < 32; ++n) {
;         const int m0 = b * 2048 + n * 64, rowb = m0 + 16 * ti + 4 * lq;
;         __builtin_amdgcn_sched_barrier(0);
;         if (n + 1 < 32) scan_load(nxt, n + 1, b, h, ti, s, li, lq, ucol, Qg, Kg, Vg, KT, QK, GC);
;         __builtin_amdgcn_sched_barrier(0);
;         const bf16x8 (&wA)[4] = cur.wA; const bf16x8 (&qA)[4] = cur.qA; const bf16x8 (&qkA)[2] = cur.qkA; const bf16x8 (&kA)[2] = cur.kA;
;         const float (&uval)[4] = cur.uval; const float (&gcr)[4] = cur.gcr; const float gl = cur.gl;
;         LAS bf16* Sb = St + (n & 1) * 32 * 136;
;         { u32x2 w; w.x = cvt_pk_bf16(S0[0], S0[1]); w.y = cvt_pk_bf16(S0[2], S0[3]); *(LAS u32x2*)(Sb + li * 136 + 16 * s + 4 * lq) = w;
;           w.x = cvt_pk_bf16(S1[0], S1[1]); w.y = cvt_pk_bf16(S1[2], S1[3]); *(LAS u32x2*)(Sb + (16 + li) * 136 + 16 * s + 4 * lq) = w; }
;         LDS_BARRIER();
;         bf16x8 bS[4]; f32x4 acc = (f32x4){0.f, 0.f, 0.f, 0.f};
; #pragma unroll
;         for (int ks = 0; ks < 4; ++ks) { bS[ks] = *(const LAS bf16x8*)(Sb + (16 * c + li) * 136 + 32 * ks + 8 * lq); acc = __builtin_amdgcn_mfma_f32_16x16x32_bf16(wA[ks], bS[ks], acc, 0, 0, 0); }
;         f32x4 o = (f32x4){0.f, 0.f, 0.f, 0.f};
; #pragma unroll
;         for (int ks = 0; ks < 4; ++ks) o = __builtin_amdgcn_mfma_f32_16x16x32_bf16(qA[ks], bS[ks], o, 0, 0, 0);
;         { float vn[4], vs[4];
; #pragma unroll
;           for (int r = 0; r < 4; ++r) { vn[r] = uval[r] - acc[r]; vs[r] = vn[r] * __expf(gl - gcr[r]); }
;           u32x2 w; w.x = cvt_pk_bf16(vn[0], vn[1]); w.y = cvt_pk_bf16(vn[2], vn[3]); *(LAS u32x2*)(Vt + (16 * c + li) * 72 + 16 * ti + 4 * lq) = w;
;           w.x = cvt_pk_bf16(vs[0], vs[1]); w.y = cvt_pk_bf16(vs[2], vs[3]); *(LAS u32x2*)(Vts + (16 * c + li) * 72 + 16 * ti + 4 * lq) = w; }
;         LDS_BARRIER();
; #pragma unroll
;         for (int r = 0; r < 4; ++r) o[r] *= __expf(gcr[r]);
; #pragma unroll
;         for (int k2 = 0; k2 < 2; ++k2) { const bf16x8 bV = *(const LAS bf16x8*)(Vt + (16 * c + li) * 72 + 32 * k2 + 8 * lq); o = __builtin_amdgcn_mfma_f32_16x16x32_bf16(qkA[k2], bV, o, 0, 0, 0); }
; #pragma unroll
.LBB0_833:
	v_add_u32_e32 v86, s8, v76
	s_and_b32 s0, s17, 32
	s_mulk_i32 s0, 0x110
	s_add_i32 s0, s0, 0
	s_lshl_b32 s23, s35, 1
	s_add_i32 s1, s23, s0
	v_cvt_pk_bf16_f32 v88, v4, v5
	v_cvt_pk_bf16_f32 v89, v6, v7
	v_add3_u32 v150, s1, v90, v98
	ds_write_b64 v150, v[88:89]
	v_cvt_pk_bf16_f32 v88, v0, v1
	v_cvt_pk_bf16_f32 v89, v2, v3
	v_add3_u32 v150, s1, v91, v98
	ds_write_b64 v150, v[88:89]
	s_waitcnt lgkmcnt(0)
	s_barrier
	v_add3_u32 v88, s0, v105, v94
	ds_read_b128 v[162:165], v88
	ds_read_b128 v[166:169], v88 offset:64
	ds_read_b128 v[176:179], v55
	ds_read_b32 v108, v174
	ds_read_u16 v180, v54
	ds_read_u16 v181, v54 offset:80
	ds_read_u16 v182, v54 offset:160
	ds_read_u16 v183, v54 offset:240
	ds_read_b128 v[114:117], v51
	ds_read_b128 v[118:121], v51 offset:64
	ds_read_b128 v[122:125], v51 offset:128
	ds_read_b128 v[126:129], v51 offset:192
	s_waitcnt lgkmcnt(0)
	v_mov_b32_e32 v87, v176
	v_mov_b32_e32 v110, v177
	v_mov_b32_e32 v153, v178
	v_mov_b32_e32 v155, v179
	v_lshlrev_b32_e32 v66, 16, v180
	v_lshlrev_b32_e32 v67, 16, v181
	v_lshlrev_b32_e32 v64, 16, v182
	v_lshlrev_b32_e32 v65, 16, v183
	v_mfma_f32_16x16x32_bf16 v[114:117], v[114:117], v[162:165], 0
	v_sub_f32_e32 v89, v108, v110
	v_mul_f32_e32 v89, 0x3fb8aa3b, v89
	v_exp_f32_e32 v89, v89
	v_mfma_f32_16x16x32_bf16 v[114:117], v[118:121], v[166:169], v[114:117]
	ds_read_b128 v[118:121], v88 offset:128
	ds_read_b128 v[170:173], v88 offset:192
	ds_read_b128 v[130:133], v51 offset:17408
	ds_read_b128 v[134:137], v51 offset:17472
	ds_read_b128 v[138:141], v51 offset:17536
	ds_read_b128 v[142:145], v51 offset:17600
	ds_read_b128 v[146:149], v52
	ds_read_b128 v[158:161], v52 offset:64
	ds_read_b128 v[60:63], v53
	ds_read_b128 v[56:59], v53 offset:64
	v_sub_f32_e32 v88, v108, v87
	v_mul_f32_e32 v88, 0x3fb8aa3b, v88
	s_waitcnt lgkmcnt(9)
	v_mfma_f32_16x16x32_bf16 v[114:117], v[122:125], v[118:121], v[114:117]
	v_exp_f32_e32 v88, v88
	s_waitcnt lgkmcnt(7)
	v_mfma_f32_16x16x32_bf16 v[122:125], v[130:133], v[162:165], 0
	v_mfma_f32_16x16x32_bf16 v[114:117], v[126:129], v[170:173], v[114:117]
	v_sub_f32_e32 v126, v108, v153
	v_sub_f32_e32 v127, v108, v155
	v_mul_f32_e32 v126, 0x3fb8aa3b, v126
	v_mul_f32_e32 v127, 0x3fb8aa3b, v127
	v_exp_f32_e32 v126, v126
	v_exp_f32_e32 v127, v127
	s_waitcnt lgkmcnt(6)
	v_mfma_f32_16x16x32_bf16 v[122:125], v[134:137], v[166:169], v[122:125]
	s_nop 0
	v_add_f32_e64 v66, v66, -v114
	v_add_f32_e64 v67, v67, -v115
	v_pk_add_f32 v[64:65], v[64:65], v[116:117] neg_lo:[0,1] neg_hi:[0,1]
	v_pk_mul_f32 v[88:89], v[88:89], v[66:67]
	v_pk_mul_f32 v[114:115], v[126:127], v[64:65]
	s_waitcnt lgkmcnt(5)
	v_mfma_f32_16x16x32_bf16 v[118:121], v[138:141], v[118:121], v[122:125]
	v_cvt_pk_bf16_f32 v66, v66, v67
	v_cvt_pk_bf16_f32 v88, v88, v89
	v_cvt_pk_bf16_f32 v67, v64, v65
	v_cvt_pk_bf16_f32 v89, v114, v115
	v_mul_f32_e32 v64, 0x3fb8aa3b, v87
	ds_write_b64 v100, v[88:89] offset:22016
	v_exp_f32_e32 v88, v64
	v_mul_f32_e32 v64, 0x3fb8aa3b, v110
	ds_write_b64 v101, v[66:67] offset:17408
	v_exp_f32_e32 v89, v64
	v_mul_f32_e32 v64, 0x3fb8aa3b, v153
	s_waitcnt lgkmcnt(0)
	s_barrier
	v_exp_f32_e32 v122, v64
	v_mul_f32_e32 v64, 0x3fb8aa3b, v155
	v_add_u32_e32 v110, v106, v94
	v_exp_f32_e32 v123, v64
	ds_read_b128 v[64:67], v110 offset:17408
	v_mfma_f32_16x16x32_bf16 v[114:117], v[142:145], v[170:173], v[118:121]
	v_ashrrev_i32_e32 v87, 31, v86
	s_nop 1
	ds_read_b128 v[118:121], v110 offset:17472
	s_nop 3
	v_pk_mul_f32 v[114:115], v[88:89], v[114:115]
	v_pk_mul_f32 v[116:117], v[122:123], v[116:117]
	v_lshlrev_b64 v[88:89], 11, v[86:87]
	v_lshl_add_u64 v[88:89], v[74:75], 0, v[88:89]
	s_waitcnt lgkmcnt(1)
	v_mfma_f32_16x16x32_bf16 v[64:67], v[146:149], v[64:67], v[114:117]
	s_waitcnt lgkmcnt(0)
	v_mfma_f32_16x16x32_bf16 v[64:67], v[158:161], v[118:121], v[64:67]
	s_nop 7
	v_cvt_pk_bf16_f32 v114, v64, s0
	global_store_short v[88:89], v114, off
	v_mul_f32_e32 v88, v64, v64
	s_nop 1
	v_mov_b32_dpp v88, v88 row_ror:8 row_mask:0xf bank_mask:0xf bound_ctrl:1
	v_fmac_f32_e32 v88, v64, v64
	s_nop 1
	v_add_f32_dpp v64, v88, v88 row_ror:4 row_mask:0xf bank_mask:0xf bound_ctrl:1
	s_nop 1
	v_add_f32_dpp v64, v64, v64 row_ror:2 row_mask:0xf bank_mask:0xf bound_ctrl:1
	s_nop 1
	v_mov_b32_dpp v88, v64 row_ror:1 row_mask:0xf bank_mask:0xf bound_ctrl:1
	s_and_saveexec_b64 s[0:1], vcc
	s_cbranch_execz .LBB0_835
	v_add_f32_e32 v64, v64, v88
	v_lshlrev_b64 v[88:89], 8, v[86:87]
	v_lshl_add_u64 v[88:89], s[18:19], 0, v[88:89]
	global_store_dword v[88:89], v64, off

; #define LAS __attribute__((address_space(3)))
; __device__ __forceinline__ void scan_unit(LAS unsigned char* lds, int uidx, const bf16* Qg, const bf16* Kg, bf16* Vg, const bf16* KT, const bf16* QK, const float* GC, float* SSQ, float* sp_gdn) {
;     ...
;         const float eg = __expf(gl); S0 = S0 * eg; S1 = S1 * eg;
; #pragma unroll
;         for (int k2 = 0; k2 < 2; ++k2) { const bf16x8 b0 = *(const LAS bf16x8*)(Vts + li * 72 + 32 * k2 + 8 * lq), b1 = *(const LAS bf16x8*)(Vts + (16 + li) * 72 + 32 * k2 + 8 * lq);
;             S0 = __builtin_amdgcn_mfma_f32_16x16x32_bf16(kA[k2], b0, S0, 0, 0, 0); S1 = __builtin_amdgcn_mfma_f32_16x16x32_bf16(kA[k2], b1, S1, 0, 0, 0); }
;         __builtin_amdgcn_sched_barrier(0);
;         cur = nxt;
;     }
.LBB0_841:
	s_or_b64 exec, exec, s[0:1]
	v_mul_f32_e32 v64, 0x3fb8aa3b, v108
	v_exp_f32_e32 v108, v64
	ds_read_b128 v[64:67], v99 offset:22016
	ds_read_b128 v[86:89], v99 offset:24320
	ds_read_b128 v[114:117], v99 offset:22080
	ds_read_b128 v[118:121], v99 offset:24384
	v_pk_mul_f32 v[6:7], v[6:7], v[108:109] op_sel_hi:[1,0]
	v_pk_mul_f32 v[4:5], v[4:5], v[108:109] op_sel_hi:[1,0]
	v_pk_mul_f32 v[2:3], v[2:3], v[108:109] op_sel_hi:[1,0]
	v_pk_mul_f32 v[0:1], v[0:1], v[108:109] op_sel_hi:[1,0]
	s_waitcnt lgkmcnt(3)
	v_mfma_f32_16x16x32_bf16 v[4:7], v[60:63], v[64:67], v[4:7]
	s_waitcnt lgkmcnt(2)
	v_mfma_f32_16x16x32_bf16 v[0:3], v[60:63], v[86:89], v[0:3]
	s_waitcnt lgkmcnt(1)
	v_mfma_f32_16x16x32_bf16 v[4:7], v[56:59], v[114:117], v[4:7]
	s_waitcnt lgkmcnt(0)
	v_mfma_f32_16x16x32_bf16 v[0:3], v[56:59], v[118:121], v[0:3]
	s_cmpk_gt_u32 s8, 0x780
	s_cbranch_scc1 .Lscan_nostage
	s_waitcnt vmcnt(8)
	ds_write_b128 v47, v[8:11]
	ds_write_b128 v47, v[12:15] offset:8704
	ds_write_b128 v47, v[16:19] offset:17408
	ds_write_b128 v47, v[20:23] offset:26112
	ds_write_b128 v48, v[24:27]
	ds_write_b128 v48, v[28:31] offset:9216
	ds_write_b128 v48, v[32:35] offset:18432
	ds_write_b128 v49, v[36:39]
	ds_write_b32 v50, v40
	s_cmpk_gt_u32 s8, 0x740
	s_cbranch_scc1 .Lscan_nostage
	s_add_u32 s24, s24, 0x20000
	s_addc_u32 s25, s25, 0
	s_add_u32 s26, s26, 0x20000
	s_addc_u32 s27, s27, 0
	s_add_u32 s28, s28, 0x20000
	s_addc_u32 s29, s29, 0
	s_add_u32 s30, s30, 0x10000
	s_addc_u32 s31, s31, 0
	s_add_u32 s98, s98, 0x20000
	s_addc_u32 s99, s99, 0
	s_add_u32 s100, s100, 0x800
	s_addc_u32 s101, s101, 0
	global_load_dwordx4 v[8:11], v41, s[24:25]
	global_load_dwordx4 v[12:15], v42, s[24:25]
	global_load_dwordx4 v[16:19], v41, s[26:27]
	global_load_dwordx4 v[20:23], v42, s[26:27]
	global_load_dwordx4 v[24:27], v43, s[28:29]
	global_load_dwordx4 v[28:31], v44, s[28:29]
	global_load_dwordx4 v[32:35], v43, s[30:31]
	global_load_dwordx4 v[36:39], v45, s[98:99]
	global_load_dword v40, v46, s[100:101]
.Lscan_nostage:
	s_add_i32 s17, s17, 32
	s_add_i32 s8, s8, 64
	s_cmpk_eq_i32 s8, 0x800
	s_cbranch_scc0 .LBB0_833
	s_branch .Lscan_store

; __global__ void __launch_bounds__(NWAVES * 64, 2) mega_fwd(Args args) {
	.amdhsa_kernel _Z8mega_fwd4Args
		.amdhsa_group_segment_fixed_size 0
		.amdhsa_private_segment_fixed_size 0
		.amdhsa_kernarg_size 544
		.amdhsa_user_sgpr_count 2
		.amdhsa_user_sgpr_dispatch_ptr 0
		.amdhsa_user_sgpr_queue_ptr 0
		.amdhsa_user_sgpr_kernarg_segment_ptr 1
		.amdhsa_user_sgpr_dispatch_id 0
		.amdhsa_user_sgpr_kernarg_preload_length 0
		.amdhsa_user_sgpr_kernarg_preload_offset 0
		.amdhsa_user_sgpr_private_segment_size 0
		.amdhsa_uses_dynamic_stack 0
		.amdhsa_enable_private_segment 0
		.amdhsa_system_sgpr_workgroup_id_x 1
		.amdhsa_system_sgpr_workgroup_id_y 0
		.amdhsa_system_sgpr_workgroup_id_z 0
		.amdhsa_system_sgpr_workgroup_info 0
		.amdhsa_system_vgpr_workitem_id 2
		.amdhsa_next_free_vgpr 245
		.amdhsa_next_free_sgpr 102
		.amdhsa_accum_offset 248
		.amdhsa_reserve_vcc 1
		.amdhsa_float_round_mode_32 0
		.amdhsa_float_round_mode_16_64 0
		.amdhsa_float_denorm_mode_32 3
		.amdhsa_float_denorm_mode_16_64 3
		.amdhsa_dx10_clamp 1
		.amdhsa_ieee_mode 1
		.amdhsa_fp16_overflow 0
		.amdhsa_tg_split 0
		.amdhsa_exception_fp_ieee_invalid_op 0
		.amdhsa_exception_fp_denorm_src 0
		.amdhsa_exception_fp_ieee_div_zero 0
		.amdhsa_exception_fp_ieee_overflow 0
		.amdhsa_exception_fp_ieee_underflow 0
		.amdhsa_exception_fp_ieee_inexact 0
		.amdhsa_exception_int_div_zero 0
	.end_amdhsa_kernel

; __global__ void __launch_bounds__(NWAVES * 64, 2) mega_fwd(Args args) {
amdhsa.kernels:
  - .agpr_count:     0
    .args:
      - .offset:         0
        .size:           288
        .value_kind:     by_value
      - .offset:         288
        .size:           4
        .value_kind:     hidden_block_count_x
      - .offset:         292
        .size:           4
        .value_kind:     hidden_block_count_y
      - .offset:         296
        .size:           4
        .value_kind:     hidden_block_count_z
      - .offset:         300
        .size:           2
        .value_kind:     hidden_group_size_x
      - .offset:         302
        .size:           2
        .value_kind:     hidden_group_size_y
      - .offset:         304
        .size:           2
        .value_kind:     hidden_group_size_z
      - .offset:         306
        .size:           2
        .value_kind:     hidden_remainder_x
      - .offset:         308
        .size:           2
        .value_kind:     hidden_remainder_y
      - .offset:         310
        .size:           2
        .value_kind:     hidden_remainder_z
      - .offset:         328
        .size:           8
        .value_kind:     hidden_global_offset_x
      - .offset:         336
        .size:           8
        .value_kind:     hidden_global_offset_y
      - .offset:         344
        .size:           8
        .value_kind:     hidden_global_offset_z
      - .offset:         352
        .size:           2
        .value_kind:     hidden_grid_dims
      - .offset:         376
        .size:           8
        .value_kind:     hidden_multigrid_sync_arg
      - .offset:         408
        .size:           4
        .value_kind:     hidden_dynamic_lds_size
    .group_segment_fixed_size: 0
    .kernarg_segment_align: 8
    .kernarg_segment_size: 544
    .language:       OpenCL C
    .language_version:
      - 2
      - 0
    .max_flat_workgroup_size: 512
    .name:           _Z8mega_fwd4Args
    .private_segment_fixed_size: 0
    .sgpr_count:     108
    .sgpr_spill_count: 27
    .symbol:         _Z8mega_fwd4Args.kd
    .uniform_work_group_size: 1
    .uses_dynamic_stack: false
    .vgpr_count:     245
    .vgpr_spill_count: 0
    .wavefront_size: 64
